# stack10 plus attention steady-loop dead adds, pads and m0 save-restore removed; unit-end barrier no longer waits for the O stores
# speedup vs baseline: 1.0020x; 1.0020x over previous
; #define ATT_WAITBAR() asm volatile("s_waitcnt vmcnt(0) lgkmcnt(0)\n\ts_barrier" ::: "memory")
; __device__ __forceinline__ void unit(int b, int h, int qb, const Params& P, LAS unsigned char* lds, const int tid) {
;     ...
;     ATT_WAITBAR();
; __global__ void __launch_bounds__(512, 2) mk_fwd(Args a) {
;     ...
;                 for (int i = 0; i < niter; ++i) {
;                     int bh, qb;
;                     if (G == 256) { const int base = 32 * ((i >> 1) & 1) + (vcu & 31); bh = 2 * (vcu >> 5) + (i >> 2); qb = (i & 1) ? base : 127 - base; }
;                     else { const int u = bx + i * G; if (u >= 2048) break; bh = u >> 7; qb = 127 - (u & 127); }
;                     att::unit(bh >> 3, bh & 7, qb, P, C.lds, C.tid);
.LBB0_35:
	s_waitcnt lgkmcnt(0)
	s_barrier
	s_add_i32 s29, s29, 1
	s_cmp_eq_u32 s29, s28
	s_cselect_b64 s[18:19], -1, 0

; #define LAS __attribute__((address_space(3)))
; __device__ __forceinline__ unsigned cvtpk_s(float lo, float hi) { return cvt_pk_bf16(lo, hi); }
; template <bool SLOW> ...
;     ...
;     bf16x8 kf[8];
; #pragma unroll
;     for (int d0 = 0; d0 < 4; ++d0) { LAS const unsigned char* kp = ((d0 & 1) ? kb : ka) + (d0 >> 1) * 512; kf[d0] = *(LAS const bf16x8*)(kp); }
; #pragma unroll
;     for (int d0 = 0; d0 < 4; ++d0) { LAS const unsigned char* kp = ((d0 & 1) ? kb : ka) + (d0 >> 1) * 512; kf[4 + d0] = *(LAS const bf16x8*)(kp + 4096); }
;     __builtin_amdgcn_s_setprio(2);
;     p0 = ATT_MFMA(kf[0], qr[0], negm);
; #pragma unroll
;     for (int d0 = 1; d0 < 4; ++d0) p0 = ATT_MFMA(kf[d0], qr[d0], p0);
;     if (!SLOW) __builtin_amdgcn_sched_barrier(0);
;     if (SLOW) {
;         p1 = ATT_MFMA(kf[4], qr[0], negm);
; #pragma unroll
;         for (int d0 = 1; d0 < 4; ++d0) p1 = ATT_MFMA(kf[4 + d0], qr[d0], p1);
;         __builtin_amdgcn_s_setprio(0);
;         __builtin_amdgcn_sched_barrier(0);
;     }
;     if (SLOW) {
;         int dq = qpos - kv0 - 4 * hi; asm volatile("" : "+v"(dq));
; #pragma unroll
;         for (int r = 0; r < 16; ++r) { const int cr = (r & 3) + 8 * (r >> 2); p0[r] = (cr > dq) ? -INFINITY : p0[r]; p1[r] = (cr + 32 > dq) ? -INFINITY : p1[r]; }
;     }
;     if (SLOW && first) {
;         float rm = fmaxf(p0[0], p1[0]);
; #pragma unroll
;         for (int r = 1; r < 16; ++r) rm = fmaxf(rm, fmaxf(p0[r], p1[r]));
;         rm = fmaxf(rm, __shfl_xor(rm, 32));
; #pragma unroll
;         for (int r = 0; r < 16; ++r) { p0[r] -= rm; p1[r] -= rm; negm[r] = -rm; }
;     }
;     float sa = 0.f, sb = 0.f;
;     if (!SLOW) {
; #pragma unroll
;         for (int g = 0; g < 4; ++g) {
;             p1 = (g == 0) ? ATT_MFMA(kf[4], qr[0], negm) : ATT_MFMA(kf[4 + g], qr[g], p1);
; #pragma unroll
;             for (int r = 4 * g; r < 4 * g + 4; r += 2) { p0[r] = __builtin_amdgcn_exp2f(p0[r]); p0[r + 1] = __builtin_amdgcn_exp2f(p0[r + 1]); sa = fadd_s(sa, p0[r]); sb = fadd_s(sb, p0[r + 1]); }
;             if (g & 1) { const int w = g >> 1;
; #pragma unroll
;                 for (int k = 0; k < 4; ++k) pw[w][k] = cvtpk_s(p0[8 * w + 2 * k], p0[8 * w + 2 * k + 1]); }
;             dma_piece(dma, g);
;             __builtin_amdgcn_sched_barrier(0);
;         }
;         l += sa + sb;
;         __builtin_amdgcn_s_setprio(0);
;     } else {
; #pragma unroll
.LBB0_58:
	s_add_i32 s12, s78, 0xffff8000
	s_cmp_lg_u32 s78, 0
	s_cselect_b32 s12, s12, 0x18000
	s_add_i32 s12, s12, 0
	s_add_i32 s13, s12, s59
	s_add_i32 s24, s18, s12
	s_add_i32 s12, s78, 0
	v_add_u32_e32 v96, s12, v143
	v_add_u32_e32 v97, s12, v171
	ds_read_b128 v[80:83], v96
	ds_read_b128 v[84:87], v97
	ds_read_b128 v[88:91], v96 offset:512
	ds_read_b128 v[92:95], v97 offset:512
	ds_read_b128 v[128:131], v96 offset:4096
	ds_read_b128 v[132:135], v97 offset:4096
	ds_read_b128 v[174:177], v96 offset:4608
	ds_read_b128 v[178:181], v97 offset:4608
	v_add_u32_e32 v149, s12, v167
	s_setprio 2
	s_waitcnt lgkmcnt(7)
	v_mfma_f32_32x32x16_bf16 v[96:111], v[80:83], v[112:115], v[64:79]
	s_waitcnt lgkmcnt(6)
	v_mfma_f32_32x32x16_bf16 v[96:111], v[84:87], v[116:119], v[96:111]
	s_waitcnt lgkmcnt(5)
	v_mfma_f32_32x32x16_bf16 v[96:111], v[88:91], v[120:123], v[96:111]
	s_waitcnt lgkmcnt(4)
	v_mfma_f32_32x32x16_bf16 v[96:111], v[92:95], v[124:127], v[96:111]
	s_waitcnt lgkmcnt(3)
	v_mfma_f32_32x32x16_bf16 v[80:95], v[128:131], v[112:115], v[64:79]
	s_nop 9
	v_exp_f32_e32 v96, v96
	v_exp_f32_e32 v97, v97
	v_exp_f32_e32 v98, v98
	v_exp_f32_e32 v99, v99
	s_mov_b32 m0, s13
	s_nop 0
	global_load_lds_dwordx4 v[150:151], off
	v_add_f32_e32 v128, v98, v96
	v_add_f32_e32 v129, v99, v97
	s_waitcnt lgkmcnt(2)
	v_mfma_f32_32x32x16_bf16 v[80:95], v[132:135], v[116:119], v[80:95]
	v_exp_f32_e32 v100, v100
	v_exp_f32_e32 v101, v101
	v_exp_f32_e32 v102, v102
	v_exp_f32_e32 v103, v103
	v_add_f32_e32 v128, v100, v128
	v_add_f32_e32 v129, v101, v129
	v_cvt_pk_bf16_f32 v96, v96, v97
	v_cvt_pk_bf16_f32 v97, v98, v99
	v_cvt_pk_bf16_f32 v98, v100, v101
	v_lshl_add_u64 v[100:101], v[150:151], 0, s[16:17]
	s_add_i32 s12, s13, 0x2000
	s_mov_b32 m0, s12
	s_nop 0
	global_load_lds_dwordx4 v[100:101], off
	v_cvt_pk_bf16_f32 v99, v102, v103
	v_add_f32_e32 v128, v102, v128
	v_add_f32_e32 v129, v103, v129
	s_waitcnt lgkmcnt(1)
	v_mfma_f32_32x32x16_bf16 v[80:95], v[174:177], v[120:123], v[80:95]
	v_exp_f32_e32 v100, v104
	v_exp_f32_e32 v101, v105
	v_exp_f32_e32 v104, v106
	v_exp_f32_e32 v105, v107
	v_add_f32_e32 v102, v100, v128
	v_add_f32_e32 v103, v101, v129
	s_mov_b32 m0, s24
	s_nop 0
	global_load_lds_dwordx4 v[152:153], off
	v_add_f32_e32 v102, v104, v102
	v_add_f32_e32 v103, v105, v103
	s_waitcnt lgkmcnt(0)
	v_mfma_f32_32x32x16_bf16 v[80:95], v[178:181], v[124:127], v[80:95]
	v_exp_f32_e32 v106, v108
	v_exp_f32_e32 v107, v109
	v_exp_f32_e32 v108, v110
	v_exp_f32_e32 v109, v111
	v_add_f32_e32 v102, v106, v102
	v_add_f32_e32 v103, v107, v103
	v_cvt_pk_bf16_f32 v100, v100, v101
	v_cvt_pk_bf16_f32 v101, v104, v105
	v_lshl_add_u64 v[104:105], v[152:153], 0, s[0:1]
	s_add_i32 s12, s24, 0x400
	s_mov_b32 m0, s12
	s_nop 0
	global_load_lds_dwordx4 v[104:105], off
	v_add_f32_e32 v110, v108, v102
	v_add_f32_e32 v111, v109, v103
	v_cvt_pk_bf16_f32 v102, v106, v107
	v_cvt_pk_bf16_f32 v103, v108, v109
	v_add_f32_e32 v104, v110, v111
	v_add_f32_e32 v173, v173, v104
	s_setprio 0
	ds_read_b64_tr_b16 v[104:105], v149 offset:16384
	ds_read_b64_tr_b16 v[106:107], v149 offset:16896
	ds_read_b64_tr_b16 v[108:109], v149 offset:20480
	ds_read_b64_tr_b16 v[110:111], v149 offset:20992
	ds_read_b64_tr_b16 v[132:133], v149 offset:24576
	ds_read_b64_tr_b16 v[134:135], v149 offset:25088
	ds_read_b64_tr_b16 v[128:129], v149 offset:28672
	ds_read_b64_tr_b16 v[130:131], v149 offset:29184
	s_waitcnt vmcnt(8) lgkmcnt(0)
	s_barrier
; #define LAS __attribute__((address_space(3)))
; __device__ __forceinline__ unsigned cvtpk_s(float lo, float hi) { return cvt_pk_bf16(lo, hi); }
; #define ATT_MFMA(a, b, c) __builtin_amdgcn_mfma_f32_32x32x16_bf16(a, b, c, 0, 0, 0)
; __device__ __forceinline__ float fadd_s(float a, float b) { float r = a + b; asm("" : "+v"(r)); return r; }
; #define ATT_VRD(j) do { lo[j] = vtr(vb + ((j) & 3) * 4096 + ((j) >> 2) * 1024); hh[j] = vtr(vb + ((j) & 3) * 4096 + ((j) >> 2) * 1024 + 512); } while (0)
; #define END_EVEN() asm volatile("s_waitcnt lgkmcnt(0)\n\ts_barrier" ::: "memory")
; #define END_ODD8() asm volatile("s_waitcnt vmcnt(8) lgkmcnt(0)\n\ts_barrier" ::: "memory")
; __device__ __forceinline__ void stepY(f32x16 (&o)[4], u32x4 (&pw)[4], f32x16& p1, float& l, LAS const unsigned char* vb, const s16x4 (&vlo)[4], const s16x4 (&vhh)[4], const DmaT& dma) {
;     __builtin_amdgcn_sched_barrier(0);
;     s16x4 lo[16], hh[16];
;     ...
; #pragma unroll
;     for (int j = 0; j < 4; ++j) { lo[j] = vlo[j]; hh[j] = vhh[j]; }
;     float sa = 0.f, sb = 0.f;
; #pragma unroll
;     for (int j = 0; j < 16; ++j) {
;         if (j + 4 < 16) ATT_VRD(j + 4);
;         { const bf16x8 vf = (bf16x8){lo[j][0], lo[j][1], lo[j][2], lo[j][3], hh[j][0], hh[j][1], hh[j][2], hh[j][3]};
;           o[j & 3] = ATT_MFMA(__builtin_bit_cast(bf16x8, pw[j >> 2]), vf, o[j & 3]); }
;         if (j < 8) { p1[2 * j] = __builtin_amdgcn_exp2f(p1[2 * j]); p1[2 * j + 1] = __builtin_amdgcn_exp2f(p1[2 * j + 1]); sa = fadd_s(sa, p1[2 * j]); sb = fadd_s(sb, p1[2 * j + 1]); }
;         if (j == 3 || j == 7) { const int w = j >> 2;
; #pragma unroll
;             for (int k = 0; k < 4; ++k) pw[2 + w][k] = cvtpk_s(p1[8 * w + 2 * k], p1[8 * w + 2 * k + 1]); }
;         if (j >= 8 && j < 12) dma_piece(dma, j - 8);
;         __builtin_amdgcn_sched_barrier(0);
;     }
;     ...
;     l += sa + sb;
; }
; template <int GRP>
; __device__ __forceinline__ void run_tiles(f32x16 (&o)[4], float& l, const bf16x8 (&qr)[4], LAS unsigned char* lds, const unsigned ldsbase, const bf16_t* ksrc, const bf16_t* vsrc, int wid, int NT, int qa, int qpos, int hi, int kA, int kB, int voff) {
;     ...
;         else          { stepX<false>(pw, p1k, l, negm, qr, lds + sc + kA, lds + sc + kB, 64 * t, qpos, hi, false, lds + sc + voff, vlo, vhh, dma); END_ODD8(); stepY(o, pw, p1k, l, lds + sc + voff, vlo, vhh, dma_off); END_EVEN(); }
;         sc = NXT(sc);
	s_setprio 1
	s_waitcnt lgkmcnt(6)
	v_mfma_f32_32x32x16_bf16 v[0:15], v[96:99], v[104:107], v[0:15]
	v_exp_f32_e32 v80, v80
	ds_read_b64_tr_b16 v[174:175], v149 offset:17408
	ds_read_b64_tr_b16 v[176:177], v149 offset:17920
	v_exp_f32_e32 v81, v81
	s_waitcnt lgkmcnt(6)
	v_mfma_f32_32x32x16_bf16 v[16:31], v[96:99], v[108:111], v[16:31]
	v_exp_f32_e32 v82, v82
	ds_read_b64_tr_b16 v[178:179], v149 offset:21504
	ds_read_b64_tr_b16 v[180:181], v149 offset:22016
	v_exp_f32_e32 v83, v83
	v_add_f32_e32 v186, v82, v80
	v_add_f32_e32 v187, v83, v81
	s_waitcnt lgkmcnt(6)
	v_mfma_f32_32x32x16_bf16 v[32:47], v[96:99], v[132:135], v[32:47]
	v_exp_f32_e32 v84, v84
	ds_read_b64_tr_b16 v[182:183], v149 offset:25600
	ds_read_b64_tr_b16 v[184:185], v149 offset:26112
	v_exp_f32_e32 v85, v85
	v_add_f32_e32 v190, v84, v186
	v_add_f32_e32 v191, v85, v187
	s_waitcnt lgkmcnt(6)
	v_mfma_f32_32x32x16_bf16 v[48:63], v[96:99], v[128:131], v[48:63]
	v_exp_f32_e32 v86, v86
	ds_read_b64_tr_b16 v[186:187], v149 offset:29696
	ds_read_b64_tr_b16 v[188:189], v149 offset:30208
	v_exp_f32_e32 v87, v87
	v_cvt_pk_bf16_f32 v206, v80, v81
	v_add_f32_e32 v190, v86, v190
	v_add_f32_e32 v191, v87, v191
	v_cvt_pk_bf16_f32 v207, v82, v83
	v_cvt_pk_bf16_f32 v208, v84, v85
	v_cvt_pk_bf16_f32 v209, v86, v87
	s_waitcnt lgkmcnt(6)
	v_mfma_f32_32x32x16_bf16 v[0:15], v[100:103], v[174:177], v[0:15]
	ds_read_b64_tr_b16 v[210:211], v149 offset:18432
	ds_read_b64_tr_b16 v[212:213], v149 offset:18944
	v_exp_f32_e32 v88, v88
	v_exp_f32_e32 v89, v89
	v_add_f32_e32 v190, v88, v190
	v_add_f32_e32 v191, v89, v191
	s_waitcnt lgkmcnt(6)
	v_mfma_f32_32x32x16_bf16 v[16:31], v[100:103], v[178:181], v[16:31]
	ds_read_b64_tr_b16 v[174:175], v149 offset:22528
	ds_read_b64_tr_b16 v[176:177], v149 offset:23040
	v_exp_f32_e32 v90, v90
	v_exp_f32_e32 v91, v91
	v_add_f32_e32 v190, v90, v190
	v_add_f32_e32 v191, v91, v191
	s_waitcnt lgkmcnt(6)
	v_mfma_f32_32x32x16_bf16 v[32:47], v[100:103], v[182:185], v[32:47]
	ds_read_b64_tr_b16 v[178:179], v149 offset:26624
	ds_read_b64_tr_b16 v[180:181], v149 offset:27136
	v_exp_f32_e32 v92, v92
	v_exp_f32_e32 v93, v93
	v_add_f32_e32 v190, v92, v190
	v_add_f32_e32 v191, v93, v191
	s_waitcnt lgkmcnt(6)
	v_mfma_f32_32x32x16_bf16 v[48:63], v[100:103], v[186:189], v[48:63]
	ds_read_b64_tr_b16 v[182:183], v149 offset:30720
	ds_read_b64_tr_b16 v[184:185], v149 offset:31232
	v_exp_f32_e32 v94, v94
	v_exp_f32_e32 v95, v95
	v_cvt_pk_bf16_f32 v186, v88, v89
	v_cvt_pk_bf16_f32 v187, v90, v91
	v_add_f32_e32 v190, v94, v190
	v_add_f32_e32 v191, v95, v191
	v_cvt_pk_bf16_f32 v188, v92, v93
	v_cvt_pk_bf16_f32 v189, v94, v95
	s_setprio 0
	s_waitcnt lgkmcnt(6)
	v_mfma_f32_32x32x16_bf16 v[0:15], v[206:209], v[210:213], v[0:15]
	ds_read_b64_tr_b16 v[214:215], v149 offset:19456
	ds_read_b64_tr_b16 v[216:217], v149 offset:19968
	s_waitcnt lgkmcnt(6)
	v_mfma_f32_32x32x16_bf16 v[16:31], v[206:209], v[174:177], v[16:31]
	ds_read_b64_tr_b16 v[210:211], v149 offset:23552
	ds_read_b64_tr_b16 v[212:213], v149 offset:24064
	s_waitcnt lgkmcnt(6)
	v_mfma_f32_32x32x16_bf16 v[32:47], v[206:209], v[178:181], v[32:47]
	ds_read_b64_tr_b16 v[174:175], v149 offset:27648
	ds_read_b64_tr_b16 v[176:177], v149 offset:28160
	s_waitcnt lgkmcnt(6)
	v_mfma_f32_32x32x16_bf16 v[48:63], v[206:209], v[182:185], v[48:63]
	ds_read_b64_tr_b16 v[178:179], v149 offset:31744
	ds_read_b64_tr_b16 v[180:181], v149 offset:32256
	s_waitcnt lgkmcnt(6)
	v_mfma_f32_32x32x16_bf16 v[0:15], v[186:189], v[214:217], v[0:15]
	s_waitcnt lgkmcnt(4)
	v_mfma_f32_32x32x16_bf16 v[16:31], v[186:189], v[210:213], v[16:31]
	s_waitcnt lgkmcnt(2)
	v_mfma_f32_32x32x16_bf16 v[32:47], v[186:189], v[174:177], v[32:47]
	s_waitcnt lgkmcnt(0)
	v_mfma_f32_32x32x16_bf16 v[48:63], v[186:189], v[178:181], v[48:63]
	s_add_i32 s12, s78, 0x8000
	s_waitcnt lgkmcnt(0)
	s_barrier
	s_cmp_lg_u32 s78, 0x18000
	v_add_f32_e32 v149, v190, v191
	s_cselect_b32 s78, s12, 0
	s_add_i32 s19, s19, -1
	v_lshl_add_u64 v[150:151], v[150:151], 0, s[50:51]
	v_lshl_add_u64 v[152:153], v[152:153], 0, s[50:51]
	s_cmp_eq_u32 s19, 0
	v_add_f32_e32 v173, v173, v149
	s_cbranch_scc0 .LBB0_58
	s_add_i32 s80, s66, -1
	s_cmp_ge_i32 s80, s70
	s_cbranch_scc0 .LBB0_61
	s_branch .LBB0_78

; #define LAS __attribute__((address_space(3)))
; __device__ __forceinline__ unsigned cvtpk_s(float lo, float hi) { return cvt_pk_bf16(lo, hi); }
; template <bool SLOW> ...
;     ...
;     bf16x8 kf[8];
; #pragma unroll
;     for (int d0 = 0; d0 < 4; ++d0) { LAS const unsigned char* kp = ((d0 & 1) ? kb : ka) + (d0 >> 1) * 512; kf[d0] = *(LAS const bf16x8*)(kp); }
; #pragma unroll
;     for (int d0 = 0; d0 < 4; ++d0) { LAS const unsigned char* kp = ((d0 & 1) ? kb : ka) + (d0 >> 1) * 512; kf[4 + d0] = *(LAS const bf16x8*)(kp + 4096); }
;     __builtin_amdgcn_s_setprio(2);
;     p0 = ATT_MFMA(kf[0], qr[0], negm);
; #pragma unroll
;     for (int d0 = 1; d0 < 4; ++d0) p0 = ATT_MFMA(kf[d0], qr[d0], p0);
;     if (!SLOW) __builtin_amdgcn_sched_barrier(0);
;     if (SLOW) {
;         p1 = ATT_MFMA(kf[4], qr[0], negm);
; #pragma unroll
;         for (int d0 = 1; d0 < 4; ++d0) p1 = ATT_MFMA(kf[4 + d0], qr[d0], p1);
;         __builtin_amdgcn_s_setprio(0);
;         __builtin_amdgcn_sched_barrier(0);
;     }
;     if (SLOW) {
;         int dq = qpos - kv0 - 4 * hi; asm volatile("" : "+v"(dq));
; #pragma unroll
;         for (int r = 0; r < 16; ++r) { const int cr = (r & 3) + 8 * (r >> 2); p0[r] = (cr > dq) ? -INFINITY : p0[r]; p1[r] = (cr + 32 > dq) ? -INFINITY : p1[r]; }
;     }
;     if (SLOW && first) {
;         float rm = fmaxf(p0[0], p1[0]);
; #pragma unroll
;         for (int r = 1; r < 16; ++r) rm = fmaxf(rm, fmaxf(p0[r], p1[r]));
;         rm = fmaxf(rm, __shfl_xor(rm, 32));
; #pragma unroll
;         for (int r = 0; r < 16; ++r) { p0[r] -= rm; p1[r] -= rm; negm[r] = -rm; }
;     }
;     float sa = 0.f, sb = 0.f;
;     if (!SLOW) {
; #pragma unroll
;         for (int g = 0; g < 4; ++g) {
;             p1 = (g == 0) ? ATT_MFMA(kf[4], qr[0], negm) : ATT_MFMA(kf[4 + g], qr[g], p1);
; #pragma unroll
;             for (int r = 4 * g; r < 4 * g + 4; r += 2) { p0[r] = __builtin_amdgcn_exp2f(p0[r]); p0[r + 1] = __builtin_amdgcn_exp2f(p0[r + 1]); sa = fadd_s(sa, p0[r]); sb = fadd_s(sb, p0[r + 1]); }
;             if (g & 1) { const int w = g >> 1;
; #pragma unroll
;                 for (int k = 0; k < 4; ++k) pw[w][k] = cvtpk_s(p0[8 * w + 2 * k], p0[8 * w + 2 * k + 1]); }
;             dma_piece(dma, g);
;             __builtin_amdgcn_sched_barrier(0);
;         }
;         l += sa + sb;
;         __builtin_amdgcn_s_setprio(0);
;     } else {
; #pragma unroll
.LBB0_93:
	s_add_i32 s12, s54, 0xffff8000
	s_cmp_lg_u32 s54, 0
	s_cselect_b32 s12, s12, 0x18000
	s_add_i32 s12, s12, 0
	s_add_i32 s25, s12, s59
	s_add_i32 s24, s18, s12
	s_add_i32 s12, s54, 0
	v_add_u32_e32 v96, s12, v143
	v_add_u32_e32 v97, s12, v171
	ds_read_b128 v[80:83], v96
	ds_read_b128 v[84:87], v97
	ds_read_b128 v[88:91], v96 offset:512
	ds_read_b128 v[92:95], v97 offset:512
	ds_read_b128 v[128:131], v96 offset:4096
	ds_read_b128 v[132:135], v97 offset:4096
	ds_read_b128 v[150:153], v96 offset:4608
	ds_read_b128 v[174:177], v97 offset:4608
	v_add_u32_e32 v147, s12, v167
	s_setprio 2
	s_waitcnt lgkmcnt(7)
	v_mfma_f32_32x32x16_bf16 v[96:111], v[80:83], v[112:115], v[64:79]
	s_waitcnt lgkmcnt(6)
	v_mfma_f32_32x32x16_bf16 v[96:111], v[84:87], v[116:119], v[96:111]
	s_waitcnt lgkmcnt(5)
	v_mfma_f32_32x32x16_bf16 v[96:111], v[88:91], v[120:123], v[96:111]
	s_waitcnt lgkmcnt(4)
	v_mfma_f32_32x32x16_bf16 v[96:111], v[92:95], v[124:127], v[96:111]
	s_waitcnt lgkmcnt(3)
	v_mfma_f32_32x32x16_bf16 v[80:95], v[128:131], v[112:115], v[64:79]
	s_nop 9
	v_exp_f32_e32 v96, v96
	v_exp_f32_e32 v97, v97
	v_exp_f32_e32 v98, v98
	v_exp_f32_e32 v99, v99
	v_add_f32_e32 v128, v98, v96
	v_add_f32_e32 v129, v99, v97
	s_waitcnt lgkmcnt(2)
	v_mfma_f32_32x32x16_bf16 v[80:95], v[132:135], v[116:119], v[80:95]
	v_exp_f32_e32 v100, v100
	v_exp_f32_e32 v101, v101
	v_exp_f32_e32 v102, v102
	v_exp_f32_e32 v103, v103
	v_add_f32_e32 v128, v100, v128
	v_add_f32_e32 v129, v101, v129
	v_cvt_pk_bf16_f32 v96, v96, v97
	v_add_f32_e32 v128, v102, v128
	v_add_f32_e32 v129, v103, v129
	v_cvt_pk_bf16_f32 v97, v98, v99
	v_cvt_pk_bf16_f32 v98, v100, v101
	v_cvt_pk_bf16_f32 v99, v102, v103
	s_waitcnt lgkmcnt(1)
	v_mfma_f32_32x32x16_bf16 v[80:95], v[150:153], v[120:123], v[80:95]
	v_exp_f32_e32 v100, v104
	v_exp_f32_e32 v101, v105
	v_exp_f32_e32 v104, v106
	v_exp_f32_e32 v105, v107
	v_add_f32_e32 v102, v100, v128
	v_add_f32_e32 v103, v101, v129
	v_add_f32_e32 v102, v104, v102
	v_add_f32_e32 v103, v105, v103
	s_waitcnt lgkmcnt(0)
	v_mfma_f32_32x32x16_bf16 v[80:95], v[174:177], v[124:127], v[80:95]
	v_exp_f32_e32 v106, v108
	v_exp_f32_e32 v107, v109
	v_exp_f32_e32 v108, v110
	v_exp_f32_e32 v109, v111
	v_add_f32_e32 v102, v106, v102
	v_add_f32_e32 v103, v107, v103
	v_cvt_pk_bf16_f32 v100, v100, v101
	v_add_f32_e32 v110, v108, v102
	v_add_f32_e32 v111, v109, v103
	v_cvt_pk_bf16_f32 v101, v104, v105
	v_cvt_pk_bf16_f32 v102, v106, v107
	v_cvt_pk_bf16_f32 v103, v108, v109
	v_add_f32_e32 v104, v110, v111
	v_add_f32_e32 v173, v173, v104
	s_setprio 0
	ds_read_b64_tr_b16 v[104:105], v147 offset:16384
	ds_read_b64_tr_b16 v[106:107], v147 offset:16896
	ds_read_b64_tr_b16 v[108:109], v147 offset:20480
	ds_read_b64_tr_b16 v[110:111], v147 offset:20992
	ds_read_b64_tr_b16 v[132:133], v147 offset:24576
	ds_read_b64_tr_b16 v[134:135], v147 offset:25088
	ds_read_b64_tr_b16 v[128:129], v147 offset:28672
	ds_read_b64_tr_b16 v[130:131], v147 offset:29184
	s_waitcnt lgkmcnt(0)
	s_barrier
; #define LAS __attribute__((address_space(3)))
; __device__ __forceinline__ unsigned cvtpk_s(float lo, float hi) { return cvt_pk_bf16(lo, hi); }
; #define ATT_MFMA(a, b, c) __builtin_amdgcn_mfma_f32_32x32x16_bf16(a, b, c, 0, 0, 0)
; __device__ __forceinline__ float fadd_s(float a, float b) { float r = a + b; asm("" : "+v"(r)); return r; }
; #define END_EVEN() asm volatile("s_waitcnt lgkmcnt(0)\n\ts_barrier" ::: "memory")
; __device__ __forceinline__ void stepY(f32x16 (&o)[4], u32x4 (&pw)[4], f32x16& p1, float& l, LAS const unsigned char* vb, const s16x4 (&vlo)[4], const s16x4 (&vhh)[4], const DmaT& dma) {
;     __builtin_amdgcn_sched_barrier(0);
;     s16x4 lo[16], hh[16];
;     ...
; #pragma unroll
;     for (int j = 0; j < 4; ++j) { lo[j] = vlo[j]; hh[j] = vhh[j]; }
;     float sa = 0.f, sb = 0.f;
; #pragma unroll
;     for (int j = 0; j < 16; ++j) {
;         if (j + 4 < 16) ATT_VRD(j + 4);
;         { const bf16x8 vf = (bf16x8){lo[j][0], lo[j][1], lo[j][2], lo[j][3], hh[j][0], hh[j][1], hh[j][2], hh[j][3]};
;           o[j & 3] = ATT_MFMA(__builtin_bit_cast(bf16x8, pw[j >> 2]), vf, o[j & 3]); }
;         if (j < 8) { p1[2 * j] = __builtin_amdgcn_exp2f(p1[2 * j]); p1[2 * j + 1] = __builtin_amdgcn_exp2f(p1[2 * j + 1]); sa = fadd_s(sa, p1[2 * j]); sb = fadd_s(sb, p1[2 * j + 1]); }
;         if (j == 3 || j == 7) { const int w = j >> 2;
; #pragma unroll
;             for (int k = 0; k < 4; ++k) pw[2 + w][k] = cvtpk_s(p1[8 * w + 2 * k], p1[8 * w + 2 * k + 1]); }
;         if (j >= 8 && j < 12) dma_piece(dma, j - 8);
;         __builtin_amdgcn_sched_barrier(0);
;     }
;     ...
;     l += sa + sb;
; }
; template <int GRP>
; __device__ __forceinline__ void run_tiles(f32x16 (&o)[4], float& l, const bf16x8 (&qr)[4], LAS unsigned char* lds, const unsigned ldsbase, const bf16_t* ksrc, const bf16_t* vsrc, int wid, int NT, int qa, int qpos, int hi, int kA, int kB, int voff) {
;     ...
;         if (GRP == 0) { stepX<false>(pw, p1k, l, negm, qr, lds + sc + kA, lds + sc + kB, 64 * t, qpos, hi, false, lds + sc + voff, vlo, vhh, dma_off); END_EVEN(); stepY(o, pw, p1k, l, lds + sc + voff, vlo, vhh, dma); END_ODD8(); }
;         else          { stepX<false>(pw, p1k, l, negm, qr, lds + sc + kA, lds + sc + kB, 64 * t, qpos, hi, false, lds + sc + voff, vlo, vhh, dma); END_ODD8(); stepY(o, pw, p1k, l, lds + sc + voff, vlo, vhh, dma_off); END_EVEN(); }
;         sc = NXT(sc);
	s_setprio 1
	s_waitcnt lgkmcnt(6)
	v_mfma_f32_32x32x16_bf16 v[0:15], v[96:99], v[104:107], v[0:15]
	v_exp_f32_e32 v80, v80
	ds_read_b64_tr_b16 v[150:151], v147 offset:17408
	ds_read_b64_tr_b16 v[152:153], v147 offset:17920
	v_exp_f32_e32 v81, v81
	s_waitcnt lgkmcnt(6)
	v_mfma_f32_32x32x16_bf16 v[16:31], v[96:99], v[108:111], v[16:31]
	v_exp_f32_e32 v82, v82
	ds_read_b64_tr_b16 v[174:175], v147 offset:21504
	ds_read_b64_tr_b16 v[176:177], v147 offset:22016
	v_exp_f32_e32 v83, v83
	v_add_f32_e32 v182, v82, v80
	v_add_f32_e32 v183, v83, v81
	s_waitcnt lgkmcnt(6)
	v_mfma_f32_32x32x16_bf16 v[32:47], v[96:99], v[132:135], v[32:47]
	v_exp_f32_e32 v84, v84
	ds_read_b64_tr_b16 v[178:179], v147 offset:25600
	ds_read_b64_tr_b16 v[180:181], v147 offset:26112
	v_exp_f32_e32 v85, v85
	v_add_f32_e32 v186, v84, v182
	v_add_f32_e32 v187, v85, v183
	s_waitcnt lgkmcnt(6)
	v_mfma_f32_32x32x16_bf16 v[48:63], v[96:99], v[128:131], v[48:63]
	v_exp_f32_e32 v86, v86
	ds_read_b64_tr_b16 v[182:183], v147 offset:29696
	ds_read_b64_tr_b16 v[184:185], v147 offset:30208
	v_exp_f32_e32 v87, v87
	v_cvt_pk_bf16_f32 v188, v84, v85
	v_add_f32_e32 v190, v86, v186
	v_add_f32_e32 v191, v87, v187
	v_cvt_pk_bf16_f32 v186, v80, v81
	v_cvt_pk_bf16_f32 v187, v82, v83
	v_cvt_pk_bf16_f32 v189, v86, v87
	s_waitcnt lgkmcnt(6)
	v_mfma_f32_32x32x16_bf16 v[0:15], v[100:103], v[150:153], v[0:15]
	ds_read_b64_tr_b16 v[206:207], v147 offset:18432
	ds_read_b64_tr_b16 v[208:209], v147 offset:18944
	v_exp_f32_e32 v88, v88
	v_exp_f32_e32 v89, v89
	v_add_f32_e32 v190, v88, v190
	v_add_f32_e32 v191, v89, v191
	s_waitcnt lgkmcnt(6)
	v_mfma_f32_32x32x16_bf16 v[16:31], v[100:103], v[174:177], v[16:31]
	ds_read_b64_tr_b16 v[150:151], v147 offset:22528
	ds_read_b64_tr_b16 v[152:153], v147 offset:23040
	v_exp_f32_e32 v90, v90
	v_exp_f32_e32 v91, v91
	v_add_f32_e32 v190, v90, v190
	v_add_f32_e32 v191, v91, v191
	s_waitcnt lgkmcnt(6)
	v_mfma_f32_32x32x16_bf16 v[32:47], v[100:103], v[178:181], v[32:47]
	ds_read_b64_tr_b16 v[174:175], v147 offset:26624
	ds_read_b64_tr_b16 v[176:177], v147 offset:27136
	v_exp_f32_e32 v92, v92
	v_exp_f32_e32 v93, v93
	v_add_f32_e32 v190, v92, v190
	v_add_f32_e32 v191, v93, v191
	s_waitcnt lgkmcnt(6)
	v_mfma_f32_32x32x16_bf16 v[48:63], v[100:103], v[182:185], v[48:63]
	ds_read_b64_tr_b16 v[178:179], v147 offset:30720
	ds_read_b64_tr_b16 v[180:181], v147 offset:31232
	v_exp_f32_e32 v94, v94
	v_exp_f32_e32 v95, v95
	v_cvt_pk_bf16_f32 v182, v88, v89
	v_cvt_pk_bf16_f32 v183, v90, v91
	v_add_f32_e32 v190, v94, v190
	v_add_f32_e32 v191, v95, v191
	v_cvt_pk_bf16_f32 v184, v92, v93
	v_cvt_pk_bf16_f32 v185, v94, v95
	s_setprio 0
	s_waitcnt lgkmcnt(6)
	v_mfma_f32_32x32x16_bf16 v[0:15], v[186:189], v[206:209], v[0:15]
	ds_read_b64_tr_b16 v[210:211], v147 offset:19456
	ds_read_b64_tr_b16 v[212:213], v147 offset:19968
	s_mov_b32 m0, s25
	s_nop 0
	global_load_lds_dwordx4 v[144:145], off
	s_waitcnt lgkmcnt(6)
	v_mfma_f32_32x32x16_bf16 v[16:31], v[186:189], v[150:153], v[16:31]
	ds_read_b64_tr_b16 v[206:207], v147 offset:23552
	ds_read_b64_tr_b16 v[208:209], v147 offset:24064
	v_lshl_add_u64 v[150:151], v[144:145], 0, s[16:17]
	s_add_i32 s12, s25, 0x2000
	s_mov_b32 m0, s12
	s_nop 0
	global_load_lds_dwordx4 v[150:151], off
	s_waitcnt lgkmcnt(6)
	v_mfma_f32_32x32x16_bf16 v[32:47], v[186:189], v[174:177], v[32:47]
	ds_read_b64_tr_b16 v[150:151], v147 offset:27648
	ds_read_b64_tr_b16 v[152:153], v147 offset:28160
	s_mov_b32 m0, s24
	s_nop 0
	global_load_lds_dwordx4 v[148:149], off
	s_waitcnt lgkmcnt(6)
	v_mfma_f32_32x32x16_bf16 v[48:63], v[186:189], v[178:181], v[48:63]
	ds_read_b64_tr_b16 v[174:175], v147 offset:31744
	ds_read_b64_tr_b16 v[176:177], v147 offset:32256
	v_lshl_add_u64 v[178:179], v[148:149], 0, s[0:1]
	s_add_i32 s12, s24, 0x400
	s_mov_b32 m0, s12
	s_nop 0
	global_load_lds_dwordx4 v[178:179], off
	s_waitcnt lgkmcnt(6)
	v_mfma_f32_32x32x16_bf16 v[0:15], v[182:185], v[210:213], v[0:15]
	s_waitcnt lgkmcnt(4)
	v_mfma_f32_32x32x16_bf16 v[16:31], v[182:185], v[206:209], v[16:31]
	s_waitcnt lgkmcnt(2)
	v_mfma_f32_32x32x16_bf16 v[32:47], v[182:185], v[150:153], v[32:47]
	s_waitcnt lgkmcnt(0)
	v_mfma_f32_32x32x16_bf16 v[48:63], v[182:185], v[174:177], v[48:63]
	s_add_i32 s12, s54, 0x8000
	s_waitcnt vmcnt(8) lgkmcnt(0)
	s_barrier
	s_cmp_lg_u32 s54, 0x18000
	v_add_f32_e32 v147, v190, v191
	s_cselect_b32 s54, s12, 0
	s_add_i32 s19, s19, -1
	v_lshl_add_u64 v[144:145], v[144:145], 0, s[42:43]
	v_lshl_add_u64 v[148:149], v[148:149], 0, s[42:43]
	s_cmp_eq_u32 s19, 0
	v_add_f32_e32 v173, v173, v147
	s_cbranch_scc0 .LBB0_93
	s_add_i32 s55, s66, -1
	s_cmp_ge_i32 s55, s70
	s_cbranch_scc0 .LBB0_96
	s_branch .LBB0_112
